# P1 swiglu epilogue: rstd slot loads software-pipelined one block ahead into free registers; waits no longer cover the previous store
# baseline (speedup 1.0000x reference)
.LBB0_165:
	v_lshlrev_b32_e32 v216, 6, v152
	v_add_u32_e32 v217, 0x2000, v216
	global_load_dwordx4 v[184:187], v216, s[74:75]
	global_load_dwordx4 v[188:191], v216, s[74:75] offset:16
	global_load_dwordx4 v[192:195], v216, s[74:75] offset:32
	global_load_dwordx4 v[196:199], v216, s[74:75] offset:48
	v_ashrrev_i32_e32 v153, 31, v152
	v_lshlrev_b64 v[154:155], 6, v[152:153]
	v_lshl_add_u64 v[170:171], s[74:75], 0, v[154:155]
	s_waitcnt lgkmcnt(0)
	s_waitcnt vmcnt(0)
	v_mov_b32_e32 v154, v184
	v_mov_b32_e32 v155, v185
	v_mov_b32_e32 v156, v186
	v_mov_b32_e32 v157, v187
	v_mov_b32_e32 v162, v188
	v_mov_b32_e32 v163, v189
	v_mov_b32_e32 v164, v190
	v_mov_b32_e32 v165, v191
	v_mov_b32_e32 v166, v192
	v_mov_b32_e32 v167, v193
	v_mov_b32_e32 v168, v194
	v_mov_b32_e32 v169, v195
	v_mov_b32_e32 v170, v196
	v_mov_b32_e32 v171, v197
	v_mov_b32_e32 v172, v198
	v_mov_b32_e32 v173, v199
	global_load_dwordx4 v[200:203], v216, s[74:75] offset:1024
	global_load_dwordx4 v[204:207], v216, s[74:75] offset:1040
	global_load_dwordx4 v[208:211], v216, s[74:75] offset:1056
	global_load_dwordx4 v[212:215], v216, s[74:75] offset:1072
	v_mov_b32_e32 v174, v124
	v_mov_b32_e32 v175, v116
	v_mov_b32_e32 v116, v125
	v_mov_b32_e32 v124, v126
	v_mov_b32_e32 v125, v118
	v_mov_b32_e32 v118, v127
	v_mov_b32_e32 v126, v120
	v_mov_b32_e32 v127, v112
	v_mov_b32_e32 v112, v121
	v_mov_b32_e32 v176, v122
	v_mov_b32_e32 v177, v114
	v_mov_b32_e32 v114, v123
	s_lshl_b32 s24, s24, 7
	v_mov_b64_e32 v[120:121], s[72:73]
	s_ashr_i32 s25, s24, 31
	v_mad_i64_i32 v[122:123], s[26:27], v152, s51, v[120:121]
	s_lshl_b64 s[24:25], s[24:25], 1
	v_lshl_add_u64 v[122:123], v[122:123], 0, s[24:25]
	v_lshl_add_u64 v[122:123], v[122:123], 0, s[6:7]
	v_mov_b32_e32 v178, v155
	v_mov_b32_e32 v179, v156
	v_mov_b32_e32 v155, v157
	v_mov_b32_e32 v156, v163
	v_mov_b32_e32 v157, v164
	v_mov_b32_e32 v163, v165
	v_pk_add_f32 v[154:155], v[178:179], v[154:155]
	v_pk_add_f32 v[156:157], v[156:157], v[162:163]
	v_pk_add_f32 v[154:155], v[154:155], v[154:155] op_sel:[0,1] op_sel_hi:[1,0]
	v_pk_add_f32 v[156:157], v[156:157], v[156:157] op_sel:[0,1] op_sel_hi:[1,0]
	v_add_f32_e32 v164, v166, v167
	v_add_f32_e32 v166, v168, v169
	v_mov_b32_e32 v165, v172
	v_mov_b32_e32 v167, v173
	v_mov_b32_e32 v155, v170
	v_mov_b32_e32 v157, v171
	v_pk_add_f32 v[162:163], v[164:165], v[166:167]
	v_pk_add_f32 v[154:155], v[154:155], v[156:157]
	s_nop 0
	v_pk_add_f32 v[154:155], v[154:155], v[162:163]
	s_nop 0
	v_add_f32_e32 v153, v154, v155
	v_fmamk_f32 v153, v153, 0x3a800000, v160
	v_rsq_f32_e32 v154, v153
	s_nop 0
	v_pk_mul_f32 v[116:117], v[116:117], v[154:155] op_sel_hi:[1,0]
	v_pk_mul_f32 v[124:125], v[124:125], v[154:155] op_sel_hi:[1,0]
	v_pk_mul_f32 v[118:119], v[118:119], v[154:155] op_sel_hi:[1,0]
	v_pk_mul_f32 v[126:127], v[126:127], v[154:155] op_sel_hi:[1,0]
	v_pk_mul_f32 v[156:157], v[174:175], v[154:155] op_sel_hi:[1,0]
	v_pk_mul_f32 v[112:113], v[112:113], v[154:155] op_sel_hi:[1,0]
	v_pk_mul_f32 v[162:163], v[176:177], v[154:155] op_sel_hi:[1,0]
	v_pk_mul_f32 v[114:115], v[114:115], v[154:155] op_sel_hi:[1,0]
	v_mul_f32_e32 v154, 0xbfb8aa3b, v117
	v_mul_f32_e32 v155, 0xbfb8aa3b, v125
	v_mul_f32_e32 v164, 0xbfb8aa3b, v119
	v_mul_f32_e32 v165, 0xbfb8aa3b, v127
	v_mul_f32_e32 v153, 0xbfb8aa3b, v157
	v_mul_f32_e32 v166, 0xbfb8aa3b, v113
	v_mul_f32_e32 v168, 0xbfb8aa3b, v115
	v_exp_f32_e32 v154, v154
	v_exp_f32_e32 v155, v155
	v_exp_f32_e32 v164, v164
	v_exp_f32_e32 v165, v165
	v_mul_f32_e32 v167, 0xbfb8aa3b, v163
	v_exp_f32_e32 v153, v153
	v_exp_f32_e32 v166, v166
	v_exp_f32_e32 v168, v168
	v_exp_f32_e32 v167, v167
	v_add_f32_e32 v154, 1.0, v154
	v_add_f32_e32 v155, 1.0, v155
	v_add_f32_e32 v164, 1.0, v164
	v_add_f32_e32 v165, 1.0, v165
	v_add_f32_e32 v153, 1.0, v153
	v_add_f32_e32 v166, 1.0, v166
	v_add_f32_e32 v168, 1.0, v168
	v_rcp_f32_e32 v154, v154
	v_rcp_f32_e32 v155, v155
	v_rcp_f32_e32 v164, v164
	v_rcp_f32_e32 v165, v165
	v_add_f32_e32 v167, 1.0, v167
	v_rcp_f32_e32 v153, v153
	v_rcp_f32_e32 v166, v166
	v_rcp_f32_e32 v168, v168
	v_rcp_f32_e32 v167, v167
	v_mul_f32_e32 v117, v117, v154
	v_mul_f32_e32 v125, v125, v155
	v_mul_f32_e32 v119, v119, v164
	v_mul_f32_e32 v127, v127, v165
	v_mul_f32_e32 v153, v157, v153
	v_mul_f32_e32 v113, v113, v166
	v_mul_f32_e32 v115, v115, v168
	v_mul_f32_e32 v116, v116, v117
	v_mul_f32_e32 v117, v124, v125
	v_mul_f32_e32 v118, v118, v119
	v_mul_f32_e32 v119, v126, v127
	v_or_b32_e32 v126, 16, v152
	v_mul_f32_e32 v154, v163, v167
	v_mul_f32_e32 v153, v156, v153
	v_mul_f32_e32 v124, v112, v113
	v_mul_f32_e32 v115, v114, v115
	v_cvt_pk_bf16_f32 v112, v153, v116
	v_cvt_pk_bf16_f32 v113, v117, v118
	v_lshl_add_u64 v[116:117], v[122:123], 0, v[136:137]
	v_ashrrev_i32_e32 v127, 31, v126
	v_mul_f32_e32 v125, v162, v154
	v_cvt_pk_bf16_f32 v114, v119, v124
	v_cvt_pk_bf16_f32 v115, v125, v115
	global_store_dwordx4 v[116:117], v[112:115], off
	v_mov_b32_e32 v162, v108
	v_mov_b32_e32 v163, v100
	v_lshlrev_b64 v[112:113], 6, v[126:127]
	v_lshl_add_u64 v[154:155], s[74:75], 0, v[112:113]
	s_waitcnt vmcnt(1)
	v_mov_b32_e32 v112, v200
	v_mov_b32_e32 v113, v201
	v_mov_b32_e32 v114, v202
	v_mov_b32_e32 v115, v203
	v_mov_b32_e32 v116, v204
	v_mov_b32_e32 v117, v205
	v_mov_b32_e32 v118, v206
	v_mov_b32_e32 v119, v207
	v_mov_b32_e32 v122, v208
	v_mov_b32_e32 v123, v209
	v_mov_b32_e32 v124, v210
	v_mov_b32_e32 v125, v211
	v_mov_b32_e32 v154, v212
	v_mov_b32_e32 v155, v213
	v_mov_b32_e32 v156, v214
	v_mov_b32_e32 v157, v215
	global_load_dwordx4 v[184:187], v216, s[74:75] offset:2048
	global_load_dwordx4 v[188:191], v216, s[74:75] offset:2064
	global_load_dwordx4 v[192:195], v216, s[74:75] offset:2080
	global_load_dwordx4 v[196:199], v216, s[74:75] offset:2096
	v_mov_b32_e32 v100, v109
	v_mov_b32_e32 v108, v110
	v_mov_b32_e32 v109, v102
	v_mov_b32_e32 v102, v111
	v_mov_b32_e32 v110, v104
	v_mov_b32_e32 v111, v96
	v_mov_b32_e32 v96, v105
	v_mov_b32_e32 v104, v106
	v_mov_b32_e32 v105, v98
	v_mov_b32_e32 v98, v107
	v_mov_b32_e32 v106, v113
	v_mov_b32_e32 v107, v114
	v_mov_b32_e32 v113, v115
	v_mov_b32_e32 v114, v117
	v_mov_b32_e32 v115, v118
	v_mov_b32_e32 v117, v119
	v_pk_add_f32 v[106:107], v[106:107], v[112:113]
	v_pk_add_f32 v[112:113], v[114:115], v[116:117]
	v_pk_add_f32 v[106:107], v[106:107], v[106:107] op_sel:[0,1] op_sel_hi:[1,0]
	v_pk_add_f32 v[112:113], v[112:113], v[112:113] op_sel:[0,1] op_sel_hi:[1,0]
	v_add_f32_e32 v118, v122, v123
	v_add_f32_e32 v122, v124, v125
	v_mov_b32_e32 v119, v156
	v_mov_b32_e32 v123, v157
	v_mov_b32_e32 v107, v154
	v_mov_b32_e32 v113, v155
	v_pk_add_f32 v[114:115], v[118:119], v[122:123]
	v_pk_add_f32 v[106:107], v[106:107], v[112:113]
	v_mad_i64_i32 v[112:113], s[26:27], v126, s51, v[120:121]
	v_pk_add_f32 v[106:107], v[106:107], v[114:115]
	v_lshl_add_u64 v[112:113], v[112:113], 0, s[24:25]
	v_add_f32_e32 v106, v106, v107
	v_fmamk_f32 v106, v106, 0x3a800000, v160
	v_rsq_f32_e32 v106, v106
	s_nop 0
	v_pk_mul_f32 v[100:101], v[100:101], v[106:107] op_sel_hi:[1,0]
	v_pk_mul_f32 v[108:109], v[108:109], v[106:107] op_sel_hi:[1,0]
	v_pk_mul_f32 v[114:115], v[162:163], v[106:107] op_sel_hi:[1,0]
	v_pk_mul_f32 v[102:103], v[102:103], v[106:107] op_sel_hi:[1,0]
	v_pk_mul_f32 v[110:111], v[110:111], v[106:107] op_sel_hi:[1,0]
	v_pk_mul_f32 v[96:97], v[96:97], v[106:107] op_sel_hi:[1,0]
	v_pk_mul_f32 v[104:105], v[104:105], v[106:107] op_sel_hi:[1,0]
	v_pk_mul_f32 v[98:99], v[98:99], v[106:107] op_sel_hi:[1,0]
	v_mul_f32_e32 v107, 0xbfb8aa3b, v101
	v_mul_f32_e32 v116, 0xbfb8aa3b, v109
	v_mul_f32_e32 v106, 0xbfb8aa3b, v115
	v_mul_f32_e32 v117, 0xbfb8aa3b, v103
	v_mul_f32_e32 v119, 0xbfb8aa3b, v97
	v_exp_f32_e32 v107, v107
	v_exp_f32_e32 v116, v116
	v_mul_f32_e32 v123, 0xbfb8aa3b, v99
	v_exp_f32_e32 v106, v106
	v_exp_f32_e32 v117, v117
	v_exp_f32_e32 v119, v119
	v_mul_f32_e32 v118, 0xbfb8aa3b, v111
	v_mul_f32_e32 v122, 0xbfb8aa3b, v105
	v_exp_f32_e32 v123, v123
	v_exp_f32_e32 v118, v118
	v_exp_f32_e32 v122, v122
	v_add_f32_e32 v107, 1.0, v107
	v_add_f32_e32 v116, 1.0, v116
	v_add_f32_e32 v106, 1.0, v106
	v_add_f32_e32 v117, 1.0, v117
	v_add_f32_e32 v119, 1.0, v119
	v_rcp_f32_e32 v107, v107
	v_rcp_f32_e32 v116, v116
	v_add_f32_e32 v123, 1.0, v123
	v_rcp_f32_e32 v106, v106
	v_rcp_f32_e32 v117, v117
	v_rcp_f32_e32 v119, v119
	v_add_f32_e32 v118, 1.0, v118
	v_add_f32_e32 v122, 1.0, v122
	v_rcp_f32_e32 v123, v123
	v_rcp_f32_e32 v118, v118
	v_rcp_f32_e32 v122, v122
	v_mul_f32_e32 v101, v101, v107
	v_mul_f32_e32 v107, v109, v116
	v_mul_f32_e32 v106, v115, v106
	v_mul_f32_e32 v103, v103, v117
	v_mul_f32_e32 v97, v97, v119
	v_mul_f32_e32 v100, v100, v101
	v_mul_f32_e32 v101, v108, v107
	v_mul_f32_e32 v99, v99, v123
	v_mul_f32_e32 v106, v114, v106
	v_mul_f32_e32 v102, v102, v103
	v_mul_f32_e32 v107, v96, v97
	v_cvt_pk_bf16_f32 v96, v106, v100
	v_cvt_pk_bf16_f32 v97, v101, v102
	v_lshl_add_u64 v[100:101], v[112:113], 0, s[6:7]
	v_or_b32_e32 v112, 32, v152
	v_mul_f32_e32 v109, v111, v118
	v_mul_f32_e32 v105, v105, v122
	v_mul_f32_e32 v99, v98, v99
	v_lshl_add_u64 v[100:101], v[100:101], 0, v[136:137]
	v_ashrrev_i32_e32 v113, 31, v112
	v_mul_f32_e32 v103, v110, v109
	v_mul_f32_e32 v104, v104, v105
	v_cvt_pk_bf16_f32 v98, v103, v107
	v_cvt_pk_bf16_f32 v99, v104, v99
	global_store_dwordx4 v[100:101], v[96:99], off
	v_mov_b32_e32 v114, v92
	v_mov_b32_e32 v92, v94
	v_lshlrev_b64 v[96:97], 6, v[112:113]
	v_lshl_add_u64 v[108:109], s[74:75], 0, v[96:97]
	s_waitcnt vmcnt(1)
	v_mov_b32_e32 v96, v184
	v_mov_b32_e32 v97, v185
	v_mov_b32_e32 v98, v186
	v_mov_b32_e32 v99, v187
	v_mov_b32_e32 v100, v188
	v_mov_b32_e32 v101, v189
	v_mov_b32_e32 v102, v190
	v_mov_b32_e32 v103, v191
	v_mov_b32_e32 v104, v192
	v_mov_b32_e32 v105, v193
	v_mov_b32_e32 v106, v194
	v_mov_b32_e32 v107, v195
	v_mov_b32_e32 v108, v196
	v_mov_b32_e32 v109, v197
	v_mov_b32_e32 v110, v198
	v_mov_b32_e32 v111, v199
	global_load_dwordx4 v[200:203], v216, s[74:75] offset:3072
	global_load_dwordx4 v[204:207], v216, s[74:75] offset:3088
	global_load_dwordx4 v[208:211], v216, s[74:75] offset:3104
	global_load_dwordx4 v[212:215], v216, s[74:75] offset:3120
	v_mov_b32_e32 v94, v80
	v_mov_b32_e32 v80, v82
	v_mov_b32_e32 v115, v88
	v_mov_b32_e32 v88, v93
	v_mov_b32_e32 v93, v90
	v_mov_b32_e32 v90, v95
	v_mov_b32_e32 v95, v84
	v_mov_b32_e32 v84, v81
	v_mov_b32_e32 v81, v86
	v_mov_b32_e32 v86, v83
	v_mov_b32_e32 v116, v97
	v_mov_b32_e32 v117, v98
	v_mov_b32_e32 v97, v99
	v_mov_b32_e32 v98, v101
	v_mov_b32_e32 v99, v102
	v_mov_b32_e32 v101, v103
	v_pk_add_f32 v[96:97], v[116:117], v[96:97]
	v_pk_add_f32 v[98:99], v[98:99], v[100:101]
	v_pk_add_f32 v[96:97], v[96:97], v[96:97] op_sel:[0,1] op_sel_hi:[1,0]
	v_pk_add_f32 v[98:99], v[98:99], v[98:99] op_sel:[0,1] op_sel_hi:[1,0]
	v_add_f32_e32 v102, v104, v105
	v_add_f32_e32 v104, v106, v107
	v_mov_b32_e32 v103, v110
	v_mov_b32_e32 v105, v111
	v_mov_b32_e32 v97, v108
	v_mov_b32_e32 v99, v109
	v_pk_add_f32 v[100:101], v[102:103], v[104:105]
	v_pk_add_f32 v[96:97], v[96:97], v[98:99]
	s_nop 0
	v_pk_add_f32 v[96:97], v[96:97], v[100:101]
	s_nop 0
	v_add_f32_e32 v82, v96, v97
	v_fmamk_f32 v82, v82, 0x3a800000, v160
	v_rsq_f32_e32 v82, v82
	v_mad_i64_i32 v[96:97], s[26:27], v112, s51, v[120:121]
	v_pk_mul_f32 v[98:99], v[114:115], v[82:83] op_sel_hi:[1,0]
	v_pk_mul_f32 v[88:89], v[88:89], v[82:83] op_sel_hi:[1,0]
	v_pk_mul_f32 v[92:93], v[92:93], v[82:83] op_sel_hi:[1,0]
	v_pk_mul_f32 v[90:91], v[90:91], v[82:83] op_sel_hi:[1,0]
	v_pk_mul_f32 v[94:95], v[94:95], v[82:83] op_sel_hi:[1,0]
	v_pk_mul_f32 v[84:85], v[84:85], v[82:83] op_sel_hi:[1,0]
	v_pk_mul_f32 v[80:81], v[80:81], v[82:83] op_sel_hi:[1,0]
	v_pk_mul_f32 v[82:83], v[86:87], v[82:83] op_sel_hi:[1,0]
	v_mul_f32_e32 v103, 0xbfb8aa3b, v85
	v_mul_f32_e32 v104, 0xbfb8aa3b, v81
	v_mul_f32_e32 v105, 0xbfb8aa3b, v83
	v_mul_f32_e32 v86, 0xbfb8aa3b, v99
	v_mul_f32_e32 v87, 0xbfb8aa3b, v89
	v_mul_f32_e32 v100, 0xbfb8aa3b, v93
	v_mul_f32_e32 v101, 0xbfb8aa3b, v91
	v_mul_f32_e32 v102, 0xbfb8aa3b, v95
	v_exp_f32_e32 v103, v103
	v_exp_f32_e32 v104, v104
	v_exp_f32_e32 v105, v105
	v_exp_f32_e32 v86, v86
	v_exp_f32_e32 v87, v87
	v_exp_f32_e32 v100, v100
	v_exp_f32_e32 v101, v101
	v_exp_f32_e32 v102, v102
	v_add_f32_e32 v103, 1.0, v103
	v_add_f32_e32 v104, 1.0, v104
	v_add_f32_e32 v105, 1.0, v105
	v_add_f32_e32 v86, 1.0, v86
	v_add_f32_e32 v87, 1.0, v87
	v_add_f32_e32 v100, 1.0, v100
	v_add_f32_e32 v101, 1.0, v101
	v_add_f32_e32 v102, 1.0, v102
	v_rcp_f32_e32 v103, v103
	v_rcp_f32_e32 v104, v104
	v_rcp_f32_e32 v105, v105
	v_rcp_f32_e32 v86, v86
	v_rcp_f32_e32 v87, v87
	v_rcp_f32_e32 v100, v100
	v_rcp_f32_e32 v101, v101
	v_rcp_f32_e32 v102, v102
	v_mul_f32_e32 v85, v85, v103
	v_mul_f32_e32 v81, v81, v104
	v_mul_f32_e32 v83, v83, v105
	v_mul_f32_e32 v86, v99, v86
	v_mul_f32_e32 v87, v89, v87
	v_mul_f32_e32 v89, v93, v100
	v_mul_f32_e32 v91, v91, v101
	v_mul_f32_e32 v93, v95, v102
	v_mul_f32_e32 v84, v84, v85
	v_mul_f32_e32 v85, v80, v81
	v_mul_f32_e32 v83, v82, v83
	v_mul_f32_e32 v86, v98, v86
	v_mul_f32_e32 v87, v88, v87
	v_mul_f32_e32 v88, v92, v89
	v_mul_f32_e32 v89, v90, v91
	v_mul_f32_e32 v90, v94, v93
	v_cvt_pk_bf16_f32 v80, v86, v87
	v_cvt_pk_bf16_f32 v81, v88, v89
	v_cvt_pk_bf16_f32 v82, v90, v84
	v_cvt_pk_bf16_f32 v83, v85, v83
	v_lshl_add_u64 v[84:85], v[96:97], 0, s[24:25]
	v_lshl_add_u64 v[84:85], v[84:85], 0, s[6:7]
	v_or_b32_e32 v96, 48, v152
	v_lshl_add_u64 v[84:85], v[84:85], 0, v[136:137]
	v_ashrrev_i32_e32 v97, 31, v96
	global_store_dwordx4 v[84:85], v[80:83], off
	v_mov_b32_e32 v98, v76
	v_mov_b32_e32 v99, v72
	v_lshlrev_b64 v[80:81], 6, v[96:97]
	v_lshl_add_u64 v[92:93], s[74:75], 0, v[80:81]
	s_waitcnt vmcnt(1)
	v_mov_b32_e32 v80, v200
	v_mov_b32_e32 v81, v201
	v_mov_b32_e32 v82, v202
	v_mov_b32_e32 v83, v203
	v_mov_b32_e32 v84, v204
	v_mov_b32_e32 v85, v205
	v_mov_b32_e32 v86, v206
	v_mov_b32_e32 v87, v207
	v_mov_b32_e32 v88, v208
	v_mov_b32_e32 v89, v209
	v_mov_b32_e32 v90, v210
	v_mov_b32_e32 v91, v211
	v_mov_b32_e32 v92, v212
	v_mov_b32_e32 v93, v213
	v_mov_b32_e32 v94, v214
	v_mov_b32_e32 v95, v215
	global_load_dwordx4 v[184:187], v217, s[74:75]
	global_load_dwordx4 v[188:191], v217, s[74:75] offset:16
	global_load_dwordx4 v[192:195], v217, s[74:75] offset:32
	global_load_dwordx4 v[196:199], v217, s[74:75] offset:48
	v_mov_b32_e32 v72, v77
	v_mov_b32_e32 v76, v78
	v_mov_b32_e32 v77, v74
	v_mov_b32_e32 v74, v79
	v_mov_b32_e32 v78, v64
	v_mov_b32_e32 v79, v68
	v_mov_b32_e32 v68, v65
	v_mov_b32_e32 v64, v81
	v_mov_b32_e32 v65, v82
	v_mov_b32_e32 v81, v83
	v_mov_b32_e32 v82, v85
	v_mov_b32_e32 v83, v86
	v_mov_b32_e32 v85, v87
	v_pk_add_f32 v[64:65], v[64:65], v[80:81]
	v_pk_add_f32 v[80:81], v[82:83], v[84:85]
	v_pk_add_f32 v[64:65], v[64:65], v[64:65] op_sel:[0,1] op_sel_hi:[1,0]
	v_pk_add_f32 v[80:81], v[80:81], v[80:81] op_sel:[0,1] op_sel_hi:[1,0]
	v_add_f32_e32 v86, v88, v89
	v_add_f32_e32 v88, v90, v91
	v_mov_b32_e32 v87, v94
	v_mov_b32_e32 v89, v95
	v_mov_b32_e32 v65, v92
	v_mov_b32_e32 v81, v93
	v_pk_add_f32 v[82:83], v[86:87], v[88:89]
	v_pk_add_f32 v[64:65], v[64:65], v[80:81]
	v_mov_b32_e32 v80, v66
	v_pk_add_f32 v[64:65], v[64:65], v[82:83]
	v_mov_b32_e32 v81, v70
	v_add_f32_e32 v64, v64, v65
	v_fmamk_f32 v64, v64, 0x3a800000, v160
	v_rsq_f32_e32 v64, v64
	v_mov_b32_e32 v70, v67
	v_pk_mul_f32 v[66:67], v[98:99], v[64:65] op_sel_hi:[1,0]
	v_pk_mul_f32 v[72:73], v[72:73], v[64:65] op_sel_hi:[1,0]
	v_pk_mul_f32 v[76:77], v[76:77], v[64:65] op_sel_hi:[1,0]
	v_pk_mul_f32 v[68:69], v[68:69], v[64:65] op_sel_hi:[1,0]
	v_pk_mul_f32 v[80:81], v[80:81], v[64:65] op_sel_hi:[1,0]
	v_pk_mul_f32 v[74:75], v[74:75], v[64:65] op_sel_hi:[1,0]
	v_pk_mul_f32 v[78:79], v[78:79], v[64:65] op_sel_hi:[1,0]
	v_pk_mul_f32 v[64:65], v[70:71], v[64:65] op_sel_hi:[1,0]
	v_mul_f32_e32 v70, 0xbfb8aa3b, v67
	v_mul_f32_e32 v71, 0xbfb8aa3b, v73
	v_mul_f32_e32 v82, 0xbfb8aa3b, v77
	v_mul_f32_e32 v85, 0xbfb8aa3b, v69
	v_mul_f32_e32 v86, 0xbfb8aa3b, v81
	v_mul_f32_e32 v83, 0xbfb8aa3b, v75
	v_mul_f32_e32 v84, 0xbfb8aa3b, v79
	v_mul_f32_e32 v87, 0xbfb8aa3b, v65
	v_exp_f32_e32 v70, v70
	v_exp_f32_e32 v71, v71
	v_exp_f32_e32 v82, v82
	v_exp_f32_e32 v85, v85
	v_exp_f32_e32 v86, v86
	v_exp_f32_e32 v83, v83
	v_exp_f32_e32 v84, v84
	v_exp_f32_e32 v87, v87
	v_add_f32_e32 v70, 1.0, v70
	v_add_f32_e32 v71, 1.0, v71
	v_add_f32_e32 v82, 1.0, v82
	v_add_f32_e32 v85, 1.0, v85
	v_add_f32_e32 v86, 1.0, v86
	v_add_f32_e32 v83, 1.0, v83
	v_add_f32_e32 v84, 1.0, v84
	v_add_f32_e32 v87, 1.0, v87
	v_rcp_f32_e32 v70, v70
	v_rcp_f32_e32 v71, v71
	v_rcp_f32_e32 v82, v82
	v_rcp_f32_e32 v85, v85
	v_rcp_f32_e32 v86, v86
	v_rcp_f32_e32 v83, v83
	v_rcp_f32_e32 v84, v84
	v_rcp_f32_e32 v87, v87
	v_mul_f32_e32 v67, v67, v70
	v_mul_f32_e32 v70, v73, v71
	v_mul_f32_e32 v71, v77, v82
	v_mul_f32_e32 v69, v69, v85
	v_mul_f32_e32 v77, v81, v86
	v_mul_f32_e32 v73, v75, v83
	v_mul_f32_e32 v75, v79, v84
	v_mul_f32_e32 v65, v65, v87
	v_mul_f32_e32 v66, v66, v67
	v_mul_f32_e32 v67, v72, v70
	v_mul_f32_e32 v68, v68, v69
	v_mul_f32_e32 v69, v80, v77
	v_mul_f32_e32 v70, v76, v71
	v_mul_f32_e32 v71, v74, v73
	v_mul_f32_e32 v72, v78, v75
	v_mul_f32_e32 v73, v64, v65
	v_cvt_pk_bf16_f32 v64, v66, v67
	v_cvt_pk_bf16_f32 v65, v70, v71
	v_cvt_pk_bf16_f32 v66, v72, v68
	v_cvt_pk_bf16_f32 v67, v69, v73
	v_mad_i64_i32 v[68:69], s[26:27], v96, s51, v[120:121]
	v_lshl_add_u64 v[68:69], v[68:69], 0, s[24:25]
	v_lshl_add_u64 v[68:69], v[68:69], 0, s[6:7]
	v_add_u32_e32 v80, 0x80, v152
	v_lshl_add_u64 v[68:69], v[68:69], 0, v[136:137]
	v_ashrrev_i32_e32 v81, 31, v80
	global_store_dwordx4 v[68:69], v[64:67], off
	v_mov_b32_e32 v82, v60
	v_mov_b32_e32 v83, v56
	v_lshlrev_b64 v[64:65], 6, v[80:81]
	v_lshl_add_u64 v[76:77], s[74:75], 0, v[64:65]
	s_waitcnt vmcnt(1)
	v_mov_b32_e32 v64, v184
	v_mov_b32_e32 v65, v185
	v_mov_b32_e32 v66, v186
	v_mov_b32_e32 v67, v187
	v_mov_b32_e32 v68, v188
	v_mov_b32_e32 v69, v189
	v_mov_b32_e32 v70, v190
	v_mov_b32_e32 v71, v191
	v_mov_b32_e32 v72, v192
	v_mov_b32_e32 v73, v193
	v_mov_b32_e32 v74, v194
	v_mov_b32_e32 v75, v195
	v_mov_b32_e32 v76, v196
	v_mov_b32_e32 v77, v197
	v_mov_b32_e32 v78, v198
	v_mov_b32_e32 v79, v199
	global_load_dwordx4 v[200:203], v217, s[74:75] offset:1024
	global_load_dwordx4 v[204:207], v217, s[74:75] offset:1040
	global_load_dwordx4 v[208:211], v217, s[74:75] offset:1056
	global_load_dwordx4 v[212:215], v217, s[74:75] offset:1072
	v_mov_b32_e32 v56, v61
	v_mov_b32_e32 v60, v62
	v_mov_b32_e32 v61, v58
	v_mov_b32_e32 v58, v63
	v_mov_b32_e32 v62, v48
	v_mov_b32_e32 v63, v52
	v_mov_b32_e32 v52, v49
	v_mov_b32_e32 v48, v65
	v_mov_b32_e32 v49, v66
	v_mov_b32_e32 v65, v67
	v_mov_b32_e32 v66, v69
	v_mov_b32_e32 v67, v70
	v_mov_b32_e32 v69, v71
	v_pk_add_f32 v[48:49], v[48:49], v[64:65]
	v_pk_add_f32 v[64:65], v[66:67], v[68:69]
	v_pk_add_f32 v[48:49], v[48:49], v[48:49] op_sel:[0,1] op_sel_hi:[1,0]
	v_pk_add_f32 v[64:65], v[64:65], v[64:65] op_sel:[0,1] op_sel_hi:[1,0]
	v_add_f32_e32 v70, v72, v73
	v_add_f32_e32 v72, v74, v75
	v_mov_b32_e32 v71, v78
	v_mov_b32_e32 v73, v79
	v_mov_b32_e32 v49, v76
	v_mov_b32_e32 v65, v77
	v_pk_add_f32 v[66:67], v[70:71], v[72:73]
	v_pk_add_f32 v[48:49], v[48:49], v[64:65]
	v_mov_b32_e32 v64, v50
	v_pk_add_f32 v[48:49], v[48:49], v[66:67]
	v_mov_b32_e32 v65, v54
	v_add_f32_e32 v48, v48, v49
	v_fmamk_f32 v48, v48, 0x3a800000, v160
	v_rsq_f32_e32 v48, v48
	v_mov_b32_e32 v54, v51
	v_pk_mul_f32 v[50:51], v[82:83], v[48:49] op_sel_hi:[1,0]
	v_pk_mul_f32 v[56:57], v[56:57], v[48:49] op_sel_hi:[1,0]
	v_pk_mul_f32 v[60:61], v[60:61], v[48:49] op_sel_hi:[1,0]
	v_pk_mul_f32 v[52:53], v[52:53], v[48:49] op_sel_hi:[1,0]
	v_pk_mul_f32 v[64:65], v[64:65], v[48:49] op_sel_hi:[1,0]
	v_pk_mul_f32 v[58:59], v[58:59], v[48:49] op_sel_hi:[1,0]
	v_pk_mul_f32 v[62:63], v[62:63], v[48:49] op_sel_hi:[1,0]
	v_pk_mul_f32 v[48:49], v[54:55], v[48:49] op_sel_hi:[1,0]
	v_mul_f32_e32 v54, 0xbfb8aa3b, v51
	v_mul_f32_e32 v55, 0xbfb8aa3b, v57
	v_mul_f32_e32 v66, 0xbfb8aa3b, v61
	v_mul_f32_e32 v69, 0xbfb8aa3b, v53
	v_mul_f32_e32 v70, 0xbfb8aa3b, v65
	v_mul_f32_e32 v67, 0xbfb8aa3b, v59
	v_mul_f32_e32 v68, 0xbfb8aa3b, v63
	v_mul_f32_e32 v71, 0xbfb8aa3b, v49
	v_exp_f32_e32 v54, v54
	v_exp_f32_e32 v55, v55
	v_exp_f32_e32 v66, v66
	v_exp_f32_e32 v69, v69
	v_exp_f32_e32 v70, v70
	v_exp_f32_e32 v67, v67
	v_exp_f32_e32 v68, v68
	v_exp_f32_e32 v71, v71
	v_add_f32_e32 v54, 1.0, v54
	v_add_f32_e32 v55, 1.0, v55
	v_add_f32_e32 v66, 1.0, v66
	v_add_f32_e32 v69, 1.0, v69
	v_add_f32_e32 v70, 1.0, v70
	v_add_f32_e32 v67, 1.0, v67
	v_add_f32_e32 v68, 1.0, v68
	v_add_f32_e32 v71, 1.0, v71
	v_rcp_f32_e32 v54, v54
	v_rcp_f32_e32 v55, v55
	v_rcp_f32_e32 v66, v66
	v_rcp_f32_e32 v69, v69
	v_rcp_f32_e32 v70, v70
	v_rcp_f32_e32 v67, v67
	v_rcp_f32_e32 v68, v68
	v_rcp_f32_e32 v71, v71
	v_mul_f32_e32 v51, v51, v54
	v_mul_f32_e32 v54, v57, v55
	v_mul_f32_e32 v55, v61, v66
	v_mul_f32_e32 v53, v53, v69
	v_mul_f32_e32 v61, v65, v70
	v_mul_f32_e32 v57, v59, v67
	v_mul_f32_e32 v59, v63, v68
	v_mul_f32_e32 v49, v49, v71
	v_mul_f32_e32 v50, v50, v51
	v_mul_f32_e32 v51, v56, v54
	v_mul_f32_e32 v52, v52, v53
	v_mul_f32_e32 v53, v64, v61
	v_mul_f32_e32 v54, v60, v55
	v_mul_f32_e32 v55, v58, v57
	v_mul_f32_e32 v56, v62, v59
	v_mul_f32_e32 v57, v48, v49
	v_cvt_pk_bf16_f32 v48, v50, v51
	v_cvt_pk_bf16_f32 v49, v54, v55
	v_cvt_pk_bf16_f32 v50, v56, v52
	v_cvt_pk_bf16_f32 v51, v53, v57
	v_mad_i64_i32 v[52:53], s[26:27], v80, s51, v[120:121]
	v_lshl_add_u64 v[52:53], v[52:53], 0, s[24:25]
	v_lshl_add_u64 v[52:53], v[52:53], 0, s[6:7]
	v_add_u32_e32 v64, 0x90, v152
	v_lshl_add_u64 v[52:53], v[52:53], 0, v[136:137]
	v_ashrrev_i32_e32 v65, 31, v64
	global_store_dwordx4 v[52:53], v[48:51], off
	v_mov_b32_e32 v66, v44
	v_mov_b32_e32 v67, v40
	v_lshlrev_b64 v[48:49], 6, v[64:65]
	v_lshl_add_u64 v[60:61], s[74:75], 0, v[48:49]
	s_waitcnt vmcnt(1)
	v_mov_b32_e32 v48, v200
	v_mov_b32_e32 v49, v201
	v_mov_b32_e32 v50, v202
	v_mov_b32_e32 v51, v203
	v_mov_b32_e32 v52, v204
	v_mov_b32_e32 v53, v205
	v_mov_b32_e32 v54, v206
	v_mov_b32_e32 v55, v207
	v_mov_b32_e32 v56, v208
	v_mov_b32_e32 v57, v209
	v_mov_b32_e32 v58, v210
	v_mov_b32_e32 v59, v211
	v_mov_b32_e32 v60, v212
	v_mov_b32_e32 v61, v213
	v_mov_b32_e32 v62, v214
	v_mov_b32_e32 v63, v215
	global_load_dwordx4 v[184:187], v217, s[74:75] offset:2048
	global_load_dwordx4 v[188:191], v217, s[74:75] offset:2064
	global_load_dwordx4 v[192:195], v217, s[74:75] offset:2080
	global_load_dwordx4 v[196:199], v217, s[74:75] offset:2096
	v_mov_b32_e32 v40, v45
	v_mov_b32_e32 v44, v46
	v_mov_b32_e32 v45, v42
	v_mov_b32_e32 v42, v47
	v_mov_b32_e32 v46, v32
	v_mov_b32_e32 v47, v36
	v_mov_b32_e32 v36, v33
	v_mov_b32_e32 v32, v49
	v_mov_b32_e32 v33, v50
	v_mov_b32_e32 v49, v51
	v_mov_b32_e32 v50, v53
	v_mov_b32_e32 v51, v54
	v_mov_b32_e32 v53, v55
	v_pk_add_f32 v[32:33], v[32:33], v[48:49]
	v_pk_add_f32 v[48:49], v[50:51], v[52:53]
	v_pk_add_f32 v[32:33], v[32:33], v[32:33] op_sel:[0,1] op_sel_hi:[1,0]
	v_pk_add_f32 v[48:49], v[48:49], v[48:49] op_sel:[0,1] op_sel_hi:[1,0]
	v_add_f32_e32 v54, v56, v57
	v_add_f32_e32 v56, v58, v59
	v_mov_b32_e32 v55, v62
	v_mov_b32_e32 v57, v63
	v_mov_b32_e32 v33, v60
	v_mov_b32_e32 v49, v61
	v_pk_add_f32 v[50:51], v[54:55], v[56:57]
	v_pk_add_f32 v[32:33], v[32:33], v[48:49]
	v_mov_b32_e32 v48, v34
	v_pk_add_f32 v[32:33], v[32:33], v[50:51]
	v_mov_b32_e32 v49, v38
	v_add_f32_e32 v32, v32, v33
	v_fmamk_f32 v32, v32, 0x3a800000, v160
	v_rsq_f32_e32 v32, v32
	v_mov_b32_e32 v38, v35
	v_pk_mul_f32 v[34:35], v[66:67], v[32:33] op_sel_hi:[1,0]
	v_pk_mul_f32 v[40:41], v[40:41], v[32:33] op_sel_hi:[1,0]
	v_pk_mul_f32 v[44:45], v[44:45], v[32:33] op_sel_hi:[1,0]
	v_pk_mul_f32 v[36:37], v[36:37], v[32:33] op_sel_hi:[1,0]
	v_pk_mul_f32 v[48:49], v[48:49], v[32:33] op_sel_hi:[1,0]
	v_pk_mul_f32 v[42:43], v[42:43], v[32:33] op_sel_hi:[1,0]
	v_pk_mul_f32 v[46:47], v[46:47], v[32:33] op_sel_hi:[1,0]
	v_pk_mul_f32 v[32:33], v[38:39], v[32:33] op_sel_hi:[1,0]
	v_mul_f32_e32 v38, 0xbfb8aa3b, v35
	v_mul_f32_e32 v39, 0xbfb8aa3b, v41
	v_mul_f32_e32 v50, 0xbfb8aa3b, v45
	v_mul_f32_e32 v53, 0xbfb8aa3b, v37
	v_mul_f32_e32 v54, 0xbfb8aa3b, v49
	v_mul_f32_e32 v51, 0xbfb8aa3b, v43
	v_mul_f32_e32 v52, 0xbfb8aa3b, v47
	v_mul_f32_e32 v55, 0xbfb8aa3b, v33
	v_exp_f32_e32 v38, v38
	v_exp_f32_e32 v39, v39
	v_exp_f32_e32 v50, v50
	v_exp_f32_e32 v53, v53
	v_exp_f32_e32 v54, v54
	v_exp_f32_e32 v51, v51
	v_exp_f32_e32 v52, v52
	v_exp_f32_e32 v55, v55
	v_add_f32_e32 v38, 1.0, v38
	v_add_f32_e32 v39, 1.0, v39
	v_add_f32_e32 v50, 1.0, v50
	v_add_f32_e32 v53, 1.0, v53
	v_add_f32_e32 v54, 1.0, v54
	v_add_f32_e32 v51, 1.0, v51
	v_add_f32_e32 v52, 1.0, v52
	v_add_f32_e32 v55, 1.0, v55
	v_rcp_f32_e32 v38, v38
	v_rcp_f32_e32 v39, v39
	v_rcp_f32_e32 v50, v50
	v_rcp_f32_e32 v53, v53
	v_rcp_f32_e32 v54, v54
	v_rcp_f32_e32 v51, v51
	v_rcp_f32_e32 v52, v52
	v_rcp_f32_e32 v55, v55
	v_mul_f32_e32 v35, v35, v38
	v_mul_f32_e32 v38, v41, v39
	v_mul_f32_e32 v39, v45, v50
	v_mul_f32_e32 v37, v37, v53
	v_mul_f32_e32 v45, v49, v54
	v_mul_f32_e32 v41, v43, v51
	v_mul_f32_e32 v43, v47, v52
	v_mul_f32_e32 v33, v33, v55
	v_mul_f32_e32 v34, v34, v35
	v_mul_f32_e32 v35, v40, v38
	v_mul_f32_e32 v36, v36, v37
	v_mul_f32_e32 v37, v48, v45
	v_mul_f32_e32 v38, v44, v39
	v_mul_f32_e32 v39, v42, v41
	v_mul_f32_e32 v40, v46, v43
	v_mul_f32_e32 v41, v32, v33
	v_cvt_pk_bf16_f32 v32, v34, v35
	v_cvt_pk_bf16_f32 v33, v38, v39
	v_cvt_pk_bf16_f32 v34, v40, v36
	v_cvt_pk_bf16_f32 v35, v37, v41
	v_mad_i64_i32 v[36:37], s[26:27], v64, s51, v[120:121]
	v_lshl_add_u64 v[36:37], v[36:37], 0, s[24:25]
	v_lshl_add_u64 v[36:37], v[36:37], 0, s[6:7]
	v_add_u32_e32 v48, 0xa0, v152
	v_lshl_add_u64 v[36:37], v[36:37], 0, v[136:137]
	v_ashrrev_i32_e32 v49, 31, v48
	global_store_dwordx4 v[36:37], v[32:35], off
	v_mov_b32_e32 v50, v28
	v_mov_b32_e32 v51, v24
	v_lshlrev_b64 v[32:33], 6, v[48:49]
	v_lshl_add_u64 v[44:45], s[74:75], 0, v[32:33]
	s_waitcnt vmcnt(1)
	v_mov_b32_e32 v32, v184
	v_mov_b32_e32 v33, v185
	v_mov_b32_e32 v34, v186
	v_mov_b32_e32 v35, v187
	v_mov_b32_e32 v36, v188
	v_mov_b32_e32 v37, v189
	v_mov_b32_e32 v38, v190
	v_mov_b32_e32 v39, v191
	v_mov_b32_e32 v40, v192
	v_mov_b32_e32 v41, v193
	v_mov_b32_e32 v42, v194
	v_mov_b32_e32 v43, v195
	v_mov_b32_e32 v44, v196
	v_mov_b32_e32 v45, v197
	v_mov_b32_e32 v46, v198
	v_mov_b32_e32 v47, v199
	global_load_dwordx4 v[200:203], v217, s[74:75] offset:3072
	global_load_dwordx4 v[204:207], v217, s[74:75] offset:3088
	global_load_dwordx4 v[208:211], v217, s[74:75] offset:3104
	global_load_dwordx4 v[212:215], v217, s[74:75] offset:3120
	v_mov_b32_e32 v24, v29
	v_mov_b32_e32 v28, v30
	v_mov_b32_e32 v29, v26
	v_mov_b32_e32 v26, v31
	v_mov_b32_e32 v30, v16
	v_mov_b32_e32 v31, v20
	v_mov_b32_e32 v20, v17
	v_mov_b32_e32 v16, v33
	v_mov_b32_e32 v17, v34
	v_mov_b32_e32 v33, v35
	v_mov_b32_e32 v34, v37
	v_mov_b32_e32 v35, v38
	v_mov_b32_e32 v37, v39
	v_pk_add_f32 v[16:17], v[16:17], v[32:33]
	v_pk_add_f32 v[32:33], v[34:35], v[36:37]
	v_pk_add_f32 v[16:17], v[16:17], v[16:17] op_sel:[0,1] op_sel_hi:[1,0]
	v_pk_add_f32 v[32:33], v[32:33], v[32:33] op_sel:[0,1] op_sel_hi:[1,0]
	v_add_f32_e32 v38, v40, v41
	v_add_f32_e32 v40, v42, v43
	v_mov_b32_e32 v39, v46
	v_mov_b32_e32 v41, v47
	v_mov_b32_e32 v17, v44
	v_mov_b32_e32 v33, v45
	v_pk_add_f32 v[34:35], v[38:39], v[40:41]
	v_pk_add_f32 v[16:17], v[16:17], v[32:33]
	v_mov_b32_e32 v32, v18
	v_pk_add_f32 v[16:17], v[16:17], v[34:35]
	v_mov_b32_e32 v33, v22
	v_add_f32_e32 v16, v16, v17
	v_fmamk_f32 v16, v16, 0x3a800000, v160
	v_rsq_f32_e32 v16, v16
	v_mov_b32_e32 v22, v19
	v_pk_mul_f32 v[18:19], v[50:51], v[16:17] op_sel_hi:[1,0]
	v_pk_mul_f32 v[24:25], v[24:25], v[16:17] op_sel_hi:[1,0]
	v_pk_mul_f32 v[28:29], v[28:29], v[16:17] op_sel_hi:[1,0]
	v_pk_mul_f32 v[20:21], v[20:21], v[16:17] op_sel_hi:[1,0]
	v_pk_mul_f32 v[32:33], v[32:33], v[16:17] op_sel_hi:[1,0]
	v_pk_mul_f32 v[26:27], v[26:27], v[16:17] op_sel_hi:[1,0]
	v_pk_mul_f32 v[30:31], v[30:31], v[16:17] op_sel_hi:[1,0]
	v_pk_mul_f32 v[16:17], v[22:23], v[16:17] op_sel_hi:[1,0]
	v_mul_f32_e32 v22, 0xbfb8aa3b, v19
	v_mul_f32_e32 v23, 0xbfb8aa3b, v25
	v_mul_f32_e32 v34, 0xbfb8aa3b, v29
	v_mul_f32_e32 v37, 0xbfb8aa3b, v21
	v_mul_f32_e32 v38, 0xbfb8aa3b, v33
	v_mul_f32_e32 v35, 0xbfb8aa3b, v27
	v_mul_f32_e32 v36, 0xbfb8aa3b, v31
	v_mul_f32_e32 v39, 0xbfb8aa3b, v17
	v_exp_f32_e32 v22, v22
	v_exp_f32_e32 v23, v23
	v_exp_f32_e32 v34, v34
	v_exp_f32_e32 v37, v37
	v_exp_f32_e32 v38, v38
	v_exp_f32_e32 v35, v35
	v_exp_f32_e32 v36, v36
	v_exp_f32_e32 v39, v39
	v_add_f32_e32 v22, 1.0, v22
	v_add_f32_e32 v23, 1.0, v23
	v_add_f32_e32 v34, 1.0, v34
	v_add_f32_e32 v37, 1.0, v37
	v_add_f32_e32 v38, 1.0, v38
	v_add_f32_e32 v35, 1.0, v35
	v_add_f32_e32 v36, 1.0, v36
	v_add_f32_e32 v39, 1.0, v39
	v_rcp_f32_e32 v22, v22
	v_rcp_f32_e32 v23, v23
	v_rcp_f32_e32 v34, v34
	v_rcp_f32_e32 v37, v37
	v_rcp_f32_e32 v38, v38
	v_rcp_f32_e32 v35, v35
	v_rcp_f32_e32 v36, v36
	v_rcp_f32_e32 v39, v39
	v_mul_f32_e32 v19, v19, v22
	v_mul_f32_e32 v22, v25, v23
	v_mul_f32_e32 v23, v29, v34
	v_mul_f32_e32 v21, v21, v37
	v_mul_f32_e32 v29, v33, v38
	v_mul_f32_e32 v25, v27, v35
	v_mul_f32_e32 v27, v31, v36
	v_mul_f32_e32 v17, v17, v39
	v_mul_f32_e32 v18, v18, v19
	v_mul_f32_e32 v19, v24, v22
	v_mul_f32_e32 v20, v20, v21
	v_mul_f32_e32 v21, v32, v29
	v_mul_f32_e32 v22, v28, v23
	v_mul_f32_e32 v23, v26, v25
	v_mul_f32_e32 v24, v30, v27
	v_mul_f32_e32 v25, v16, v17
	v_cvt_pk_bf16_f32 v16, v18, v19
	v_cvt_pk_bf16_f32 v17, v22, v23
	v_cvt_pk_bf16_f32 v18, v24, v20
	v_cvt_pk_bf16_f32 v19, v21, v25
	v_mad_i64_i32 v[20:21], s[26:27], v48, s51, v[120:121]
	v_lshl_add_u64 v[20:21], v[20:21], 0, s[24:25]
	v_lshl_add_u64 v[20:21], v[20:21], 0, s[6:7]
	v_add_u32_e32 v32, 0xb0, v152
	v_lshl_add_u64 v[20:21], v[20:21], 0, v[136:137]
	v_ashrrev_i32_e32 v33, 31, v32
	global_store_dwordx4 v[20:21], v[16:19], off
	v_mov_b32_e32 v34, v12
	v_mov_b32_e32 v35, v8
	v_lshlrev_b64 v[16:17], 6, v[32:33]
	v_lshl_add_u64 v[28:29], s[74:75], 0, v[16:17]
	s_waitcnt vmcnt(1)
	v_mov_b32_e32 v16, v200
	v_mov_b32_e32 v17, v201
	v_mov_b32_e32 v18, v202
	v_mov_b32_e32 v19, v203
	v_mov_b32_e32 v20, v204
	v_mov_b32_e32 v21, v205
	v_mov_b32_e32 v22, v206
	v_mov_b32_e32 v23, v207
	v_mov_b32_e32 v24, v208
	v_mov_b32_e32 v25, v209
	v_mov_b32_e32 v26, v210
	v_mov_b32_e32 v27, v211
	v_mov_b32_e32 v28, v212
	v_mov_b32_e32 v29, v213
	v_mov_b32_e32 v30, v214
	v_mov_b32_e32 v31, v215
	v_mov_b32_e32 v8, v13
	v_mov_b32_e32 v12, v14
	v_mov_b32_e32 v13, v10
	v_mov_b32_e32 v10, v15
	v_mov_b32_e32 v14, v0
	v_mov_b32_e32 v15, v4
	v_mov_b32_e32 v4, v1
	v_mov_b32_e32 v0, v17
	v_mov_b32_e32 v1, v18
	v_mov_b32_e32 v17, v19
	v_mov_b32_e32 v18, v21
	v_mov_b32_e32 v19, v22
	v_mov_b32_e32 v21, v23
	v_pk_add_f32 v[0:1], v[0:1], v[16:17]
	v_pk_add_f32 v[16:17], v[18:19], v[20:21]
	v_pk_add_f32 v[0:1], v[0:1], v[0:1] op_sel:[0,1] op_sel_hi:[1,0]
	v_pk_add_f32 v[16:17], v[16:17], v[16:17] op_sel:[0,1] op_sel_hi:[1,0]
	v_add_f32_e32 v22, v24, v25
	v_add_f32_e32 v24, v26, v27
	v_mov_b32_e32 v23, v30
	v_mov_b32_e32 v25, v31
	v_mov_b32_e32 v1, v28
	v_mov_b32_e32 v17, v29
	v_pk_add_f32 v[18:19], v[22:23], v[24:25]
	v_pk_add_f32 v[0:1], v[0:1], v[16:17]
	v_mov_b32_e32 v16, v2
	v_pk_add_f32 v[0:1], v[0:1], v[18:19]
	v_mov_b32_e32 v17, v6
	v_add_f32_e32 v0, v0, v1
	v_fmamk_f32 v0, v0, 0x3a800000, v160
	v_rsq_f32_e32 v0, v0
	v_mov_b32_e32 v6, v3
	v_pk_mul_f32 v[2:3], v[34:35], v[0:1] op_sel_hi:[1,0]
	v_pk_mul_f32 v[8:9], v[8:9], v[0:1] op_sel_hi:[1,0]
	v_pk_mul_f32 v[12:13], v[12:13], v[0:1] op_sel_hi:[1,0]
	v_pk_mul_f32 v[4:5], v[4:5], v[0:1] op_sel_hi:[1,0]
	v_pk_mul_f32 v[16:17], v[16:17], v[0:1] op_sel_hi:[1,0]
	v_pk_mul_f32 v[10:11], v[10:11], v[0:1] op_sel_hi:[1,0]
	v_pk_mul_f32 v[14:15], v[14:15], v[0:1] op_sel_hi:[1,0]
	v_pk_mul_f32 v[0:1], v[6:7], v[0:1] op_sel_hi:[1,0]
	v_mul_f32_e32 v6, 0xbfb8aa3b, v3
	v_mul_f32_e32 v7, 0xbfb8aa3b, v9
	v_mul_f32_e32 v18, 0xbfb8aa3b, v13
	v_mul_f32_e32 v21, 0xbfb8aa3b, v5
	v_mul_f32_e32 v22, 0xbfb8aa3b, v17
	v_mul_f32_e32 v19, 0xbfb8aa3b, v11
	v_mul_f32_e32 v20, 0xbfb8aa3b, v15
	v_mul_f32_e32 v23, 0xbfb8aa3b, v1
	v_exp_f32_e32 v6, v6
	v_exp_f32_e32 v7, v7
	v_exp_f32_e32 v18, v18
	v_exp_f32_e32 v21, v21
	v_exp_f32_e32 v22, v22
	v_exp_f32_e32 v19, v19
	v_exp_f32_e32 v20, v20
	v_exp_f32_e32 v23, v23
	v_add_f32_e32 v6, 1.0, v6
	v_add_f32_e32 v7, 1.0, v7
	v_add_f32_e32 v18, 1.0, v18
	v_add_f32_e32 v21, 1.0, v21
	v_add_f32_e32 v22, 1.0, v22
	v_add_f32_e32 v19, 1.0, v19
	v_add_f32_e32 v20, 1.0, v20
	v_add_f32_e32 v23, 1.0, v23
	v_rcp_f32_e32 v6, v6
	v_rcp_f32_e32 v7, v7
	v_rcp_f32_e32 v18, v18
	v_rcp_f32_e32 v21, v21
	v_rcp_f32_e32 v22, v22
	v_rcp_f32_e32 v19, v19
	v_rcp_f32_e32 v20, v20
	v_rcp_f32_e32 v23, v23
	v_mul_f32_e32 v3, v3, v6
	v_mul_f32_e32 v6, v9, v7
	v_mul_f32_e32 v7, v13, v18
	v_mul_f32_e32 v5, v5, v21
	v_mul_f32_e32 v13, v17, v22
	v_mul_f32_e32 v9, v11, v19
	v_mul_f32_e32 v11, v15, v20
	v_mul_f32_e32 v1, v1, v23
	v_mul_f32_e32 v2, v2, v3
	v_mul_f32_e32 v3, v8, v6
	v_mul_f32_e32 v4, v4, v5
	v_mul_f32_e32 v5, v16, v13
	v_mul_f32_e32 v6, v12, v7
	v_mul_f32_e32 v7, v10, v9
	v_mul_f32_e32 v8, v14, v11
	v_mul_f32_e32 v9, v0, v1
	v_cvt_pk_bf16_f32 v0, v2, v3
	v_cvt_pk_bf16_f32 v1, v6, v7
	v_cvt_pk_bf16_f32 v2, v8, v4
	v_cvt_pk_bf16_f32 v3, v5, v9
	v_mad_i64_i32 v[4:5], s[26:27], v32, s51, v[120:121]
	v_lshl_add_u64 v[4:5], v[4:5], 0, s[24:25]
	v_lshl_add_u64 v[4:5], v[4:5], 0, s[6:7]
	v_lshl_add_u64 v[4:5], v[4:5], 0, v[136:137]
	global_store_dwordx4 v[4:5], v[0:3], off
	s_andn2_b64 vcc, exec, s[4:5]
	s_mov_b64 s[4:5], -1
	s_cbranch_vccnz .LBB0_157
	s_branch .LBB0_191
